# P3 GLA scan: software-pipelined chunk loop (two register sets, next group's 16 loads issued before current group is consumed, re-derived vmcnt)
# baseline (speedup 1.0000x reference)
; __device__ void phase_gla_scan(const P& p) {
;     ...
;     for (int n8 = 0; n8 < nc; n8 += 8) {
;       unsigned kvv[8]; float2 dd[8];
; #pragma unroll
;       for (int i = 0; i < 8; ++i) {
;         int n = n8 + i;
;         int chunk = dir == 0 ? chunk0 + n : chunk0 + nc - 1 - n;
;         size_t base = (size_t)((chunk * 4 + h) * 2 + dir);
;         kvv[i] = *(const unsigned*)(kv + base * 8192 + e0);
;         dd[i] = *(const float2*)(dec + base * 64 + dk);
;       }
.LBB0_328:
	s_add_i32 s20, s4, s8
	s_and_b64 s[22:23], s[0:1], exec
	s_cselect_b32 s21, s20, s11
	s_xor_b32 s22, s8, 0x1ffffffe
	s_lshl_b32 s21, s21, 3
	s_add_i32 s27, s22, s9
	s_or_b32 s22, s21, s10
	s_ashr_i32 s23, s22, 31
	s_add_i32 s26, s20, 1
	s_lshl_b64 s[24:25], s[22:23], 14
	s_lshl_b64 s[22:23], s[22:23], 8
	v_lshl_add_u64 v[10:11], v[0:1], 0, s[22:23]
	s_and_b64 s[22:23], s[0:1], exec
	s_cselect_b32 s21, s26, s27
	s_xor_b32 s22, s8, 0x1ffffffd
	s_lshl_b32 s21, s21, 3
	s_add_i32 s27, s22, s9
	s_or_b32 s22, s21, s10
	s_ashr_i32 s23, s22, 31
	v_lshl_add_u64 v[6:7], v[2:3], 0, s[24:25]
	s_add_i32 s26, s20, 2
	s_lshl_b64 s[24:25], s[22:23], 14
	s_lshl_b64 s[22:23], s[22:23], 8
	v_lshl_add_u64 v[14:15], v[0:1], 0, s[22:23]
	s_and_b64 s[22:23], s[0:1], exec
	s_cselect_b32 s21, s26, s27
	s_xor_b32 s22, s8, 0x1ffffffc
	s_lshl_b32 s21, s21, 3
	s_add_i32 s27, s22, s9
	s_or_b32 s22, s21, s10
	s_ashr_i32 s23, s22, 31
	v_lshl_add_u64 v[12:13], v[2:3], 0, s[24:25]
	s_add_i32 s26, s20, 3
	s_lshl_b64 s[24:25], s[22:23], 14
	s_lshl_b64 s[22:23], s[22:23], 8
	v_lshl_add_u64 v[18:19], v[0:1], 0, s[22:23]
	s_and_b64 s[22:23], s[0:1], exec
	s_cselect_b32 s21, s26, s27
	s_xor_b32 s22, s8, 0x1ffffffb
	s_lshl_b32 s21, s21, 3
	s_add_i32 s27, s22, s9
	s_or_b32 s22, s21, s10
	s_ashr_i32 s23, s22, 31
	v_lshl_add_u64 v[16:17], v[2:3], 0, s[24:25]
	s_add_i32 s26, s20, 4
	s_lshl_b64 s[24:25], s[22:23], 14
	s_lshl_b64 s[22:23], s[22:23], 8
	v_lshl_add_u64 v[22:23], v[0:1], 0, s[22:23]
	s_and_b64 s[22:23], s[0:1], exec
	s_cselect_b32 s21, s26, s27
	s_xor_b32 s22, s8, 0x1ffffffa
	s_lshl_b32 s21, s21, 3
	global_load_dword v9, v[6:7], off
	s_add_i32 s27, s22, s9
	s_or_b32 s22, s21, s10
	global_load_dwordx2 v[10:11], v[10:11], off
	s_ashr_i32 s23, s22, 31
	v_lshl_add_u64 v[20:21], v[2:3], 0, s[24:25]
	s_add_i32 s26, s20, 5
	s_lshl_b64 s[24:25], s[22:23], 14
	s_lshl_b64 s[22:23], s[22:23], 8
	global_load_dword v40, v[12:13], off
	v_lshl_add_u64 v[26:27], v[0:1], 0, s[22:23]
	s_and_b64 s[22:23], s[0:1], exec
	global_load_dwordx2 v[14:15], v[14:15], off
	s_cselect_b32 s21, s26, s27
	s_xor_b32 s22, s8, 0x1ffffff9
	s_lshl_b32 s21, s21, 3
	global_load_dword v41, v[16:17], off
	s_add_i32 s27, s22, s9
	s_or_b32 s22, s21, s10
	global_load_dwordx2 v[18:19], v[18:19], off
	s_ashr_i32 s23, s22, 31
	v_lshl_add_u64 v[24:25], v[2:3], 0, s[24:25]
	s_add_i32 s26, s20, 6
	s_lshl_b64 s[24:25], s[22:23], 14
	s_lshl_b64 s[22:23], s[22:23], 8
	global_load_dword v42, v[20:21], off
	v_lshl_add_u64 v[30:31], v[0:1], 0, s[22:23]
	s_and_b64 s[22:23], s[0:1], exec
	global_load_dwordx2 v[22:23], v[22:23], off
	s_cselect_b32 s21, s26, s27
	v_lshl_add_u64 v[28:29], v[2:3], 0, s[24:25]
	s_add_i32 s24, s20, 7
	s_xor_b32 s20, s8, 0x1ffffff8
	s_lshl_b32 s21, s21, 3
	global_load_dword v43, v[24:25], off
	s_add_i32 s25, s20, s9
	s_or_b32 s20, s21, s10
	global_load_dwordx2 v[26:27], v[26:27], off
	s_ashr_i32 s21, s20, 31
	s_lshl_b64 s[22:23], s[20:21], 14
	s_lshl_b64 s[20:21], s[20:21], 8
	global_load_dword v44, v[28:29], off
	v_lshl_add_u64 v[34:35], v[0:1], 0, s[20:21]
	s_and_b64 s[20:21], s[0:1], exec
	global_load_dwordx2 v[30:31], v[30:31], off
	s_cselect_b32 s20, s24, s25
	v_lshl_add_u64 v[32:33], v[2:3], 0, s[22:23]
	s_lshl_b32 s20, s20, 3
	global_load_dword v45, v[32:33], off
	s_or_b32 s20, s20, s10
	global_load_dwordx2 v[34:35], v[34:35], off
	s_ashr_i32 s21, s20, 31
	s_lshl_b64 s[22:23], s[20:21], 14
	s_lshl_b64 s[20:21], s[20:21], 8
	v_lshl_add_u64 v[36:37], v[2:3], 0, s[22:23]
	v_lshl_add_u64 v[38:39], v[0:1], 0, s[20:21]
	global_load_dword v46, v[36:37], off
	s_nop 0
	global_load_dwordx2 v[38:39], v[38:39], off
	s_add_i32 s8, s8, 8
	s_add_i32 s11, s11, -8
	s_add_i32 s20, s4, s8
	s_and_b64 s[22:23], s[0:1], exec
	s_cselect_b32 s21, s20, s11
	s_xor_b32 s22, s8, 0x1ffffffe
	s_lshl_b32 s21, s21, 3
	s_add_i32 s27, s22, s9
	s_or_b32 s22, s21, s10
	s_ashr_i32 s23, s22, 31
	s_add_i32 s26, s20, 1
	s_lshl_b64 s[24:25], s[22:23], 14
	s_lshl_b64 s[22:23], s[22:23], 8
	v_lshl_add_u64 v[70:71], v[0:1], 0, s[22:23]
	s_and_b64 s[22:23], s[0:1], exec
	s_cselect_b32 s21, s26, s27
	s_xor_b32 s22, s8, 0x1ffffffd
	s_lshl_b32 s21, s21, 3
	s_add_i32 s27, s22, s9
	s_or_b32 s22, s21, s10
	s_ashr_i32 s23, s22, 31
	v_lshl_add_u64 v[66:67], v[2:3], 0, s[24:25]
	s_add_i32 s26, s20, 2
	s_lshl_b64 s[24:25], s[22:23], 14
	s_lshl_b64 s[22:23], s[22:23], 8
	v_lshl_add_u64 v[74:75], v[0:1], 0, s[22:23]
	s_and_b64 s[22:23], s[0:1], exec
	s_cselect_b32 s21, s26, s27
	s_xor_b32 s22, s8, 0x1ffffffc
	s_lshl_b32 s21, s21, 3
	s_add_i32 s27, s22, s9
	s_or_b32 s22, s21, s10
	s_ashr_i32 s23, s22, 31
	v_lshl_add_u64 v[72:73], v[2:3], 0, s[24:25]
	s_add_i32 s26, s20, 3
	s_lshl_b64 s[24:25], s[22:23], 14
	s_lshl_b64 s[22:23], s[22:23], 8
	v_lshl_add_u64 v[78:79], v[0:1], 0, s[22:23]
	s_and_b64 s[22:23], s[0:1], exec
	s_cselect_b32 s21, s26, s27
	s_xor_b32 s22, s8, 0x1ffffffb
	s_lshl_b32 s21, s21, 3
	s_add_i32 s27, s22, s9
	s_or_b32 s22, s21, s10
	s_ashr_i32 s23, s22, 31
	v_lshl_add_u64 v[76:77], v[2:3], 0, s[24:25]
	s_add_i32 s26, s20, 4
	s_lshl_b64 s[24:25], s[22:23], 14
	s_lshl_b64 s[22:23], s[22:23], 8
	v_lshl_add_u64 v[82:83], v[0:1], 0, s[22:23]
	s_and_b64 s[22:23], s[0:1], exec
	s_cselect_b32 s21, s26, s27
	s_xor_b32 s22, s8, 0x1ffffffa
	s_lshl_b32 s21, s21, 3
	global_load_dword v69, v[66:67], off
	s_add_i32 s27, s22, s9
	s_or_b32 s22, s21, s10
	global_load_dwordx2 v[70:71], v[70:71], off
	s_ashr_i32 s23, s22, 31
	v_lshl_add_u64 v[80:81], v[2:3], 0, s[24:25]
	s_add_i32 s26, s20, 5
	s_lshl_b64 s[24:25], s[22:23], 14
	s_lshl_b64 s[22:23], s[22:23], 8
	global_load_dword v100, v[72:73], off
	v_lshl_add_u64 v[86:87], v[0:1], 0, s[22:23]
; __device__ __forceinline__ float bf2f(u16 h) { return __uint_as_float(((unsigned)h) << 16); }
; __device__ void phase_gla_scan(const P& p) {
;     ...
; #pragma unroll
;       for (int i = 0; i < 8; ++i) {
;         int n = n8 + i;
;         int chunk = dir == 0 ? chunk0 + n : chunk0 + nc - 1 - n;
;         size_t base = (size_t)((chunk * 4 + h) * 2 + dir);
;         *(unsigned*)(kv + base * 8192 + e0) = pack2(s0, s1);
;         s0 = dd[i].x * s0 + bf2f((u16)(kvv[i] & 0xffff));
;         s1 = dd[i].y * s1 + bf2f((u16)(kvv[i] >> 16));
;       }
;     }
	s_and_b64 s[22:23], s[0:1], exec
	global_load_dwordx2 v[74:75], v[74:75], off
	s_cselect_b32 s21, s26, s27
	s_xor_b32 s22, s8, 0x1ffffff9
	s_lshl_b32 s21, s21, 3
	global_load_dword v101, v[76:77], off
	s_add_i32 s27, s22, s9
	s_or_b32 s22, s21, s10
	global_load_dwordx2 v[78:79], v[78:79], off
	s_ashr_i32 s23, s22, 31
	v_lshl_add_u64 v[84:85], v[2:3], 0, s[24:25]
	s_add_i32 s26, s20, 6
	s_lshl_b64 s[24:25], s[22:23], 14
	s_lshl_b64 s[22:23], s[22:23], 8
	global_load_dword v102, v[80:81], off
	v_lshl_add_u64 v[90:91], v[0:1], 0, s[22:23]
	s_and_b64 s[22:23], s[0:1], exec
	global_load_dwordx2 v[82:83], v[82:83], off
	s_cselect_b32 s21, s26, s27
	v_lshl_add_u64 v[88:89], v[2:3], 0, s[24:25]
	s_add_i32 s24, s20, 7
	s_xor_b32 s20, s8, 0x1ffffff8
	s_lshl_b32 s21, s21, 3
	global_load_dword v103, v[84:85], off
	s_add_i32 s25, s20, s9
	s_or_b32 s20, s21, s10
	global_load_dwordx2 v[86:87], v[86:87], off
	s_ashr_i32 s21, s20, 31
	s_lshl_b64 s[22:23], s[20:21], 14
	s_lshl_b64 s[20:21], s[20:21], 8
	global_load_dword v104, v[88:89], off
	v_lshl_add_u64 v[94:95], v[0:1], 0, s[20:21]
	s_and_b64 s[20:21], s[0:1], exec
	global_load_dwordx2 v[90:91], v[90:91], off
	s_cselect_b32 s20, s24, s25
	v_lshl_add_u64 v[92:93], v[2:3], 0, s[22:23]
	s_lshl_b32 s20, s20, 3
	global_load_dword v105, v[92:93], off
	s_or_b32 s20, s20, s10
	global_load_dwordx2 v[94:95], v[94:95], off
	s_ashr_i32 s21, s20, 31
	s_lshl_b64 s[22:23], s[20:21], 14
	s_lshl_b64 s[20:21], s[20:21], 8
	v_lshl_add_u64 v[96:97], v[2:3], 0, s[22:23]
	v_lshl_add_u64 v[98:99], v[0:1], 0, s[20:21]
	global_load_dword v106, v[96:97], off
	s_nop 0
	global_load_dwordx2 v[98:99], v[98:99], off
	s_add_i32 s8, s8, 8
	s_add_i32 s11, s11, -8
	v_cvt_pk_bf16_f32 v47, v4, v5
	global_store_dword v[6:7], v47, off
	s_waitcnt vmcnt(32)
	v_lshlrev_b32_e32 v6, 16, v9
	v_and_b32_e32 v7, 0xffff0000, v9
	s_waitcnt vmcnt(31)
	v_pk_fma_f32 v[4:5], v[4:5], v[10:11], v[6:7]
	s_nop 0
	v_cvt_pk_bf16_f32 v6, v4, v5
	global_store_dword v[12:13], v6, off
	s_waitcnt vmcnt(31)
	v_lshlrev_b32_e32 v6, 16, v40
	v_and_b32_e32 v7, 0xffff0000, v40
	s_waitcnt vmcnt(30)
	v_pk_fma_f32 v[4:5], v[4:5], v[14:15], v[6:7]
	s_nop 0
	v_cvt_pk_bf16_f32 v6, v4, v5
	global_store_dword v[16:17], v6, off
	s_waitcnt vmcnt(30)
	v_lshlrev_b32_e32 v6, 16, v41
	v_and_b32_e32 v7, 0xffff0000, v41
	s_waitcnt vmcnt(29)
	v_pk_fma_f32 v[4:5], v[4:5], v[18:19], v[6:7]
	s_nop 0
	v_cvt_pk_bf16_f32 v6, v4, v5
	global_store_dword v[20:21], v6, off
	s_waitcnt vmcnt(29)
	v_lshlrev_b32_e32 v6, 16, v42
	v_and_b32_e32 v7, 0xffff0000, v42
	s_waitcnt vmcnt(28)
	v_pk_fma_f32 v[4:5], v[4:5], v[22:23], v[6:7]
	s_nop 0
	v_cvt_pk_bf16_f32 v6, v4, v5
	global_store_dword v[24:25], v6, off
	s_waitcnt vmcnt(28)
	v_lshlrev_b32_e32 v6, 16, v43
	v_and_b32_e32 v7, 0xffff0000, v43
	s_waitcnt vmcnt(27)
	v_pk_fma_f32 v[4:5], v[4:5], v[26:27], v[6:7]
	s_nop 0
	v_cvt_pk_bf16_f32 v6, v4, v5
	global_store_dword v[28:29], v6, off
	s_waitcnt vmcnt(27)
	v_lshlrev_b32_e32 v6, 16, v44
	v_and_b32_e32 v7, 0xffff0000, v44
	s_waitcnt vmcnt(26)
	v_pk_fma_f32 v[4:5], v[4:5], v[30:31], v[6:7]
	s_nop 0
	v_cvt_pk_bf16_f32 v6, v4, v5
	global_store_dword v[32:33], v6, off
	s_waitcnt vmcnt(26)
	v_lshlrev_b32_e32 v6, 16, v45
	v_and_b32_e32 v7, 0xffff0000, v45
	s_waitcnt vmcnt(25)
	v_pk_fma_f32 v[4:5], v[4:5], v[34:35], v[6:7]
	s_waitcnt vmcnt(24)
	v_and_b32_e32 v7, 0xffff0000, v46
	v_cvt_pk_bf16_f32 v6, v4, v5
	global_store_dword v[36:37], v6, off
	v_lshlrev_b32_e32 v6, 16, v46
	s_waitcnt vmcnt(24)
	v_pk_fma_f32 v[4:5], v[4:5], v[38:39], v[6:7]
.Lmy_scan_loop:
	s_cmp_ge_u32 s8, s5
	s_cbranch_scc1 .Lmy_scan_tail_b
	s_add_i32 s20, s4, s8
	s_and_b64 s[22:23], s[0:1], exec
	s_cselect_b32 s21, s20, s11
	s_xor_b32 s22, s8, 0x1ffffffe
	s_lshl_b32 s21, s21, 3
	s_add_i32 s27, s22, s9
	s_or_b32 s22, s21, s10
	s_ashr_i32 s23, s22, 31
	s_add_i32 s26, s20, 1
	s_lshl_b64 s[24:25], s[22:23], 14
	s_lshl_b64 s[22:23], s[22:23], 8
	v_lshl_add_u64 v[10:11], v[0:1], 0, s[22:23]
	s_and_b64 s[22:23], s[0:1], exec
	s_cselect_b32 s21, s26, s27
	s_xor_b32 s22, s8, 0x1ffffffd
	s_lshl_b32 s21, s21, 3
	s_add_i32 s27, s22, s9
	s_or_b32 s22, s21, s10
	s_ashr_i32 s23, s22, 31
	v_lshl_add_u64 v[6:7], v[2:3], 0, s[24:25]
	s_add_i32 s26, s20, 2
	s_lshl_b64 s[24:25], s[22:23], 14
	s_lshl_b64 s[22:23], s[22:23], 8
	v_lshl_add_u64 v[14:15], v[0:1], 0, s[22:23]
	s_and_b64 s[22:23], s[0:1], exec
	s_cselect_b32 s21, s26, s27
	s_xor_b32 s22, s8, 0x1ffffffc
	s_lshl_b32 s21, s21, 3
	s_add_i32 s27, s22, s9
	s_or_b32 s22, s21, s10
	s_ashr_i32 s23, s22, 31
	v_lshl_add_u64 v[12:13], v[2:3], 0, s[24:25]
	s_add_i32 s26, s20, 3
	s_lshl_b64 s[24:25], s[22:23], 14
	s_lshl_b64 s[22:23], s[22:23], 8
	v_lshl_add_u64 v[18:19], v[0:1], 0, s[22:23]
	s_and_b64 s[22:23], s[0:1], exec
	s_cselect_b32 s21, s26, s27
	s_xor_b32 s22, s8, 0x1ffffffb
	s_lshl_b32 s21, s21, 3
	s_add_i32 s27, s22, s9
	s_or_b32 s22, s21, s10
	s_ashr_i32 s23, s22, 31
	v_lshl_add_u64 v[16:17], v[2:3], 0, s[24:25]
	s_add_i32 s26, s20, 4
	s_lshl_b64 s[24:25], s[22:23], 14
	s_lshl_b64 s[22:23], s[22:23], 8
	v_lshl_add_u64 v[22:23], v[0:1], 0, s[22:23]
	s_and_b64 s[22:23], s[0:1], exec
	s_cselect_b32 s21, s26, s27
	s_xor_b32 s22, s8, 0x1ffffffa
	s_lshl_b32 s21, s21, 3
	global_load_dword v9, v[6:7], off
	s_add_i32 s27, s22, s9
	s_or_b32 s22, s21, s10
	global_load_dwordx2 v[10:11], v[10:11], off
	s_ashr_i32 s23, s22, 31
	v_lshl_add_u64 v[20:21], v[2:3], 0, s[24:25]
	s_add_i32 s26, s20, 5
	s_lshl_b64 s[24:25], s[22:23], 14
	s_lshl_b64 s[22:23], s[22:23], 8
	global_load_dword v40, v[12:13], off
	v_lshl_add_u64 v[26:27], v[0:1], 0, s[22:23]
	s_and_b64 s[22:23], s[0:1], exec
	global_load_dwordx2 v[14:15], v[14:15], off
; __device__ __forceinline__ float bf2f(u16 h) { return __uint_as_float(((unsigned)h) << 16); }
; __device__ void phase_gla_scan(const P& p) {
;     ...
;     for (int n8 = 0; n8 < nc; n8 += 8) {
;       unsigned kvv[8]; float2 dd[8];
; #pragma unroll
;       for (int i = 0; i < 8; ++i) {
;         int n = n8 + i;
;         int chunk = dir == 0 ? chunk0 + n : chunk0 + nc - 1 - n;
;         size_t base = (size_t)((chunk * 4 + h) * 2 + dir);
;         kvv[i] = *(const unsigned*)(kv + base * 8192 + e0);
;         dd[i] = *(const float2*)(dec + base * 64 + dk);
;       }
; #pragma unroll
;       for (int i = 0; i < 8; ++i) {
;         int n = n8 + i;
;         int chunk = dir == 0 ? chunk0 + n : chunk0 + nc - 1 - n;
;         size_t base = (size_t)((chunk * 4 + h) * 2 + dir);
;         *(unsigned*)(kv + base * 8192 + e0) = pack2(s0, s1);
;         s0 = dd[i].x * s0 + bf2f((u16)(kvv[i] & 0xffff));
;         s1 = dd[i].y * s1 + bf2f((u16)(kvv[i] >> 16));
;       }
;     }
	s_cselect_b32 s21, s26, s27
	s_xor_b32 s22, s8, 0x1ffffff9
	s_lshl_b32 s21, s21, 3
	global_load_dword v41, v[16:17], off
	s_add_i32 s27, s22, s9
	s_or_b32 s22, s21, s10
	global_load_dwordx2 v[18:19], v[18:19], off
	s_ashr_i32 s23, s22, 31
	v_lshl_add_u64 v[24:25], v[2:3], 0, s[24:25]
	s_add_i32 s26, s20, 6
	s_lshl_b64 s[24:25], s[22:23], 14
	s_lshl_b64 s[22:23], s[22:23], 8
	global_load_dword v42, v[20:21], off
	v_lshl_add_u64 v[30:31], v[0:1], 0, s[22:23]
	s_and_b64 s[22:23], s[0:1], exec
	global_load_dwordx2 v[22:23], v[22:23], off
	s_cselect_b32 s21, s26, s27
	v_lshl_add_u64 v[28:29], v[2:3], 0, s[24:25]
	s_add_i32 s24, s20, 7
	s_xor_b32 s20, s8, 0x1ffffff8
	s_lshl_b32 s21, s21, 3
	global_load_dword v43, v[24:25], off
	s_add_i32 s25, s20, s9
	s_or_b32 s20, s21, s10
	global_load_dwordx2 v[26:27], v[26:27], off
	s_ashr_i32 s21, s20, 31
	s_lshl_b64 s[22:23], s[20:21], 14
	s_lshl_b64 s[20:21], s[20:21], 8
	global_load_dword v44, v[28:29], off
	v_lshl_add_u64 v[34:35], v[0:1], 0, s[20:21]
	s_and_b64 s[20:21], s[0:1], exec
	global_load_dwordx2 v[30:31], v[30:31], off
	s_cselect_b32 s20, s24, s25
	v_lshl_add_u64 v[32:33], v[2:3], 0, s[22:23]
	s_lshl_b32 s20, s20, 3
	global_load_dword v45, v[32:33], off
	s_or_b32 s20, s20, s10
	global_load_dwordx2 v[34:35], v[34:35], off
	s_ashr_i32 s21, s20, 31
	s_lshl_b64 s[22:23], s[20:21], 14
	s_lshl_b64 s[20:21], s[20:21], 8
	v_lshl_add_u64 v[36:37], v[2:3], 0, s[22:23]
	v_lshl_add_u64 v[38:39], v[0:1], 0, s[20:21]
	global_load_dword v46, v[36:37], off
	s_nop 0
	global_load_dwordx2 v[38:39], v[38:39], off
	s_add_i32 s8, s8, 8
	s_add_i32 s11, s11, -8
	v_cvt_pk_bf16_f32 v107, v4, v5
	global_store_dword v[66:67], v107, off
	s_waitcnt vmcnt(40)
	v_lshlrev_b32_e32 v66, 16, v69
	v_and_b32_e32 v67, 0xffff0000, v69
	s_waitcnt vmcnt(39)
	v_pk_fma_f32 v[4:5], v[4:5], v[70:71], v[66:67]
	s_nop 0
	v_cvt_pk_bf16_f32 v66, v4, v5
	global_store_dword v[72:73], v66, off
	s_waitcnt vmcnt(39)
	v_lshlrev_b32_e32 v66, 16, v100
	v_and_b32_e32 v67, 0xffff0000, v100
	s_waitcnt vmcnt(38)
	v_pk_fma_f32 v[4:5], v[4:5], v[74:75], v[66:67]
	s_nop 0
	v_cvt_pk_bf16_f32 v66, v4, v5
	global_store_dword v[76:77], v66, off
	s_waitcnt vmcnt(38)
	v_lshlrev_b32_e32 v66, 16, v101
	v_and_b32_e32 v67, 0xffff0000, v101
	s_waitcnt vmcnt(37)
	v_pk_fma_f32 v[4:5], v[4:5], v[78:79], v[66:67]
	s_nop 0
	v_cvt_pk_bf16_f32 v66, v4, v5
	global_store_dword v[80:81], v66, off
	s_waitcnt vmcnt(37)
	v_lshlrev_b32_e32 v66, 16, v102
	v_and_b32_e32 v67, 0xffff0000, v102
	s_waitcnt vmcnt(36)
	v_pk_fma_f32 v[4:5], v[4:5], v[82:83], v[66:67]
	s_nop 0
	v_cvt_pk_bf16_f32 v66, v4, v5
	global_store_dword v[84:85], v66, off
	s_waitcnt vmcnt(36)
	v_lshlrev_b32_e32 v66, 16, v103
	v_and_b32_e32 v67, 0xffff0000, v103
	s_waitcnt vmcnt(35)
	v_pk_fma_f32 v[4:5], v[4:5], v[86:87], v[66:67]
	s_nop 0
	v_cvt_pk_bf16_f32 v66, v4, v5
	global_store_dword v[88:89], v66, off
	s_waitcnt vmcnt(35)
	v_lshlrev_b32_e32 v66, 16, v104
	v_and_b32_e32 v67, 0xffff0000, v104
	s_waitcnt vmcnt(34)
	v_pk_fma_f32 v[4:5], v[4:5], v[90:91], v[66:67]
	s_nop 0
	v_cvt_pk_bf16_f32 v66, v4, v5
	global_store_dword v[92:93], v66, off
	s_waitcnt vmcnt(34)
	v_lshlrev_b32_e32 v66, 16, v105
	v_and_b32_e32 v67, 0xffff0000, v105
	s_waitcnt vmcnt(33)
	v_pk_fma_f32 v[4:5], v[4:5], v[94:95], v[66:67]
	s_waitcnt vmcnt(32)
	v_and_b32_e32 v67, 0xffff0000, v106
	v_cvt_pk_bf16_f32 v66, v4, v5
	global_store_dword v[96:97], v66, off
	v_lshlrev_b32_e32 v66, 16, v106
	s_waitcnt vmcnt(32)
	v_pk_fma_f32 v[4:5], v[4:5], v[98:99], v[66:67]
	s_cmp_ge_u32 s8, s5
	s_cbranch_scc1 .Lmy_scan_tail_a
	s_add_i32 s20, s4, s8
	s_and_b64 s[22:23], s[0:1], exec
	s_cselect_b32 s21, s20, s11
	s_xor_b32 s22, s8, 0x1ffffffe
	s_lshl_b32 s21, s21, 3
	s_add_i32 s27, s22, s9
	s_or_b32 s22, s21, s10
	s_ashr_i32 s23, s22, 31
	s_add_i32 s26, s20, 1
	s_lshl_b64 s[24:25], s[22:23], 14
	s_lshl_b64 s[22:23], s[22:23], 8
	v_lshl_add_u64 v[70:71], v[0:1], 0, s[22:23]
	s_and_b64 s[22:23], s[0:1], exec
	s_cselect_b32 s21, s26, s27
	s_xor_b32 s22, s8, 0x1ffffffd
	s_lshl_b32 s21, s21, 3
	s_add_i32 s27, s22, s9
	s_or_b32 s22, s21, s10
	s_ashr_i32 s23, s22, 31
	v_lshl_add_u64 v[66:67], v[2:3], 0, s[24:25]
	s_add_i32 s26, s20, 2
	s_lshl_b64 s[24:25], s[22:23], 14
	s_lshl_b64 s[22:23], s[22:23], 8
	v_lshl_add_u64 v[74:75], v[0:1], 0, s[22:23]
	s_and_b64 s[22:23], s[0:1], exec
	s_cselect_b32 s21, s26, s27
	s_xor_b32 s22, s8, 0x1ffffffc
	s_lshl_b32 s21, s21, 3
	s_add_i32 s27, s22, s9
	s_or_b32 s22, s21, s10
	s_ashr_i32 s23, s22, 31
	v_lshl_add_u64 v[72:73], v[2:3], 0, s[24:25]
	s_add_i32 s26, s20, 3
	s_lshl_b64 s[24:25], s[22:23], 14
	s_lshl_b64 s[22:23], s[22:23], 8
	v_lshl_add_u64 v[78:79], v[0:1], 0, s[22:23]
	s_and_b64 s[22:23], s[0:1], exec
	s_cselect_b32 s21, s26, s27
	s_xor_b32 s22, s8, 0x1ffffffb
	s_lshl_b32 s21, s21, 3
	s_add_i32 s27, s22, s9
	s_or_b32 s22, s21, s10
	s_ashr_i32 s23, s22, 31
	v_lshl_add_u64 v[76:77], v[2:3], 0, s[24:25]
	s_add_i32 s26, s20, 4
	s_lshl_b64 s[24:25], s[22:23], 14
	s_lshl_b64 s[22:23], s[22:23], 8
	v_lshl_add_u64 v[82:83], v[0:1], 0, s[22:23]
	s_and_b64 s[22:23], s[0:1], exec
	s_cselect_b32 s21, s26, s27
	s_xor_b32 s22, s8, 0x1ffffffa
	s_lshl_b32 s21, s21, 3
	global_load_dword v69, v[66:67], off
	s_add_i32 s27, s22, s9
	s_or_b32 s22, s21, s10
	global_load_dwordx2 v[70:71], v[70:71], off
	s_ashr_i32 s23, s22, 31
	v_lshl_add_u64 v[80:81], v[2:3], 0, s[24:25]
	s_add_i32 s26, s20, 5
	s_lshl_b64 s[24:25], s[22:23], 14
	s_lshl_b64 s[22:23], s[22:23], 8
	global_load_dword v100, v[72:73], off
	v_lshl_add_u64 v[86:87], v[0:1], 0, s[22:23]
	s_and_b64 s[22:23], s[0:1], exec
	global_load_dwordx2 v[74:75], v[74:75], off
	s_cselect_b32 s21, s26, s27
; __device__ __forceinline__ float bf2f(u16 h) { return __uint_as_float(((unsigned)h) << 16); }
; __device__ void phase_gla_scan(const P& p) {
;     ...
;     for (int n8 = 0; n8 < nc; n8 += 8) {
;       unsigned kvv[8]; float2 dd[8];
; #pragma unroll
;       for (int i = 0; i < 8; ++i) {
;         int n = n8 + i;
;         int chunk = dir == 0 ? chunk0 + n : chunk0 + nc - 1 - n;
;         size_t base = (size_t)((chunk * 4 + h) * 2 + dir);
;         kvv[i] = *(const unsigned*)(kv + base * 8192 + e0);
;         dd[i] = *(const float2*)(dec + base * 64 + dk);
;       }
; #pragma unroll
;       for (int i = 0; i < 8; ++i) {
;         int n = n8 + i;
;         int chunk = dir == 0 ? chunk0 + n : chunk0 + nc - 1 - n;
;         size_t base = (size_t)((chunk * 4 + h) * 2 + dir);
;         *(unsigned*)(kv + base * 8192 + e0) = pack2(s0, s1);
;         s0 = dd[i].x * s0 + bf2f((u16)(kvv[i] & 0xffff));
;         s1 = dd[i].y * s1 + bf2f((u16)(kvv[i] >> 16));
;       }
;     }
	s_xor_b32 s22, s8, 0x1ffffff9
	s_lshl_b32 s21, s21, 3
	global_load_dword v101, v[76:77], off
	s_add_i32 s27, s22, s9
	s_or_b32 s22, s21, s10
	global_load_dwordx2 v[78:79], v[78:79], off
	s_ashr_i32 s23, s22, 31
	v_lshl_add_u64 v[84:85], v[2:3], 0, s[24:25]
	s_add_i32 s26, s20, 6
	s_lshl_b64 s[24:25], s[22:23], 14
	s_lshl_b64 s[22:23], s[22:23], 8
	global_load_dword v102, v[80:81], off
	v_lshl_add_u64 v[90:91], v[0:1], 0, s[22:23]
	s_and_b64 s[22:23], s[0:1], exec
	global_load_dwordx2 v[82:83], v[82:83], off
	s_cselect_b32 s21, s26, s27
	v_lshl_add_u64 v[88:89], v[2:3], 0, s[24:25]
	s_add_i32 s24, s20, 7
	s_xor_b32 s20, s8, 0x1ffffff8
	s_lshl_b32 s21, s21, 3
	global_load_dword v103, v[84:85], off
	s_add_i32 s25, s20, s9
	s_or_b32 s20, s21, s10
	global_load_dwordx2 v[86:87], v[86:87], off
	s_ashr_i32 s21, s20, 31
	s_lshl_b64 s[22:23], s[20:21], 14
	s_lshl_b64 s[20:21], s[20:21], 8
	global_load_dword v104, v[88:89], off
	v_lshl_add_u64 v[94:95], v[0:1], 0, s[20:21]
	s_and_b64 s[20:21], s[0:1], exec
	global_load_dwordx2 v[90:91], v[90:91], off
	s_cselect_b32 s20, s24, s25
	v_lshl_add_u64 v[92:93], v[2:3], 0, s[22:23]
	s_lshl_b32 s20, s20, 3
	global_load_dword v105, v[92:93], off
	s_or_b32 s20, s20, s10
	global_load_dwordx2 v[94:95], v[94:95], off
	s_ashr_i32 s21, s20, 31
	s_lshl_b64 s[22:23], s[20:21], 14
	s_lshl_b64 s[20:21], s[20:21], 8
	v_lshl_add_u64 v[96:97], v[2:3], 0, s[22:23]
	v_lshl_add_u64 v[98:99], v[0:1], 0, s[20:21]
	global_load_dword v106, v[96:97], off
	s_nop 0
	global_load_dwordx2 v[98:99], v[98:99], off
	s_add_i32 s8, s8, 8
	s_add_i32 s11, s11, -8
	v_cvt_pk_bf16_f32 v47, v4, v5
	global_store_dword v[6:7], v47, off
	s_waitcnt vmcnt(40)
	v_lshlrev_b32_e32 v6, 16, v9
	v_and_b32_e32 v7, 0xffff0000, v9
	s_waitcnt vmcnt(39)
	v_pk_fma_f32 v[4:5], v[4:5], v[10:11], v[6:7]
	s_nop 0
	v_cvt_pk_bf16_f32 v6, v4, v5
	global_store_dword v[12:13], v6, off
	s_waitcnt vmcnt(39)
	v_lshlrev_b32_e32 v6, 16, v40
	v_and_b32_e32 v7, 0xffff0000, v40
	s_waitcnt vmcnt(38)
	v_pk_fma_f32 v[4:5], v[4:5], v[14:15], v[6:7]
	s_nop 0
	v_cvt_pk_bf16_f32 v6, v4, v5
	global_store_dword v[16:17], v6, off
	s_waitcnt vmcnt(38)
	v_lshlrev_b32_e32 v6, 16, v41
	v_and_b32_e32 v7, 0xffff0000, v41
	s_waitcnt vmcnt(37)
	v_pk_fma_f32 v[4:5], v[4:5], v[18:19], v[6:7]
	s_nop 0
	v_cvt_pk_bf16_f32 v6, v4, v5
	global_store_dword v[20:21], v6, off
	s_waitcnt vmcnt(37)
	v_lshlrev_b32_e32 v6, 16, v42
	v_and_b32_e32 v7, 0xffff0000, v42
	s_waitcnt vmcnt(36)
	v_pk_fma_f32 v[4:5], v[4:5], v[22:23], v[6:7]
	s_nop 0
	v_cvt_pk_bf16_f32 v6, v4, v5
	global_store_dword v[24:25], v6, off
	s_waitcnt vmcnt(36)
	v_lshlrev_b32_e32 v6, 16, v43
	v_and_b32_e32 v7, 0xffff0000, v43
	s_waitcnt vmcnt(35)
	v_pk_fma_f32 v[4:5], v[4:5], v[26:27], v[6:7]
	s_nop 0
	v_cvt_pk_bf16_f32 v6, v4, v5
	global_store_dword v[28:29], v6, off
	s_waitcnt vmcnt(35)
	v_lshlrev_b32_e32 v6, 16, v44
	v_and_b32_e32 v7, 0xffff0000, v44
	s_waitcnt vmcnt(34)
	v_pk_fma_f32 v[4:5], v[4:5], v[30:31], v[6:7]
	s_nop 0
	v_cvt_pk_bf16_f32 v6, v4, v5
	global_store_dword v[32:33], v6, off
	s_waitcnt vmcnt(34)
	v_lshlrev_b32_e32 v6, 16, v45
	v_and_b32_e32 v7, 0xffff0000, v45
	s_waitcnt vmcnt(33)
	v_pk_fma_f32 v[4:5], v[4:5], v[34:35], v[6:7]
	s_waitcnt vmcnt(32)
	v_and_b32_e32 v7, 0xffff0000, v46
	v_cvt_pk_bf16_f32 v6, v4, v5
	global_store_dword v[36:37], v6, off
	v_lshlrev_b32_e32 v6, 16, v46
	s_waitcnt vmcnt(32)
	v_pk_fma_f32 v[4:5], v[4:5], v[38:39], v[6:7]
	s_branch .Lmy_scan_loop
; __device__ __forceinline__ float bf2f(u16 h) { return __uint_as_float(((unsigned)h) << 16); }
; __device__ void phase_gla_scan(const P& p) {
;     ...
;   for (int it = blockIdx.x; it < 768; it += gridDim.x) {
;     ...
; #pragma unroll
;       for (int i = 0; i < 8; ++i) {
;         int n = n8 + i;
;         int chunk = dir == 0 ? chunk0 + n : chunk0 + nc - 1 - n;
;         size_t base = (size_t)((chunk * 4 + h) * 2 + dir);
;         *(unsigned*)(kv + base * 8192 + e0) = pack2(s0, s1);
;         s0 = dd[i].x * s0 + bf2f((u16)(kvv[i] & 0xffff));
;         s1 = dd[i].y * s1 + bf2f((u16)(kvv[i] >> 16));
;       }
.Lmy_scan_tail_b:
	v_cvt_pk_bf16_f32 v107, v4, v5
	global_store_dword v[66:67], v107, off
	s_waitcnt vmcnt(24)
	v_lshlrev_b32_e32 v66, 16, v69
	v_and_b32_e32 v67, 0xffff0000, v69
	s_waitcnt vmcnt(23)
	v_pk_fma_f32 v[4:5], v[4:5], v[70:71], v[66:67]
	s_nop 0
	v_cvt_pk_bf16_f32 v66, v4, v5
	global_store_dword v[72:73], v66, off
	s_waitcnt vmcnt(23)
	v_lshlrev_b32_e32 v66, 16, v100
	v_and_b32_e32 v67, 0xffff0000, v100
	s_waitcnt vmcnt(22)
	v_pk_fma_f32 v[4:5], v[4:5], v[74:75], v[66:67]
	s_nop 0
	v_cvt_pk_bf16_f32 v66, v4, v5
	global_store_dword v[76:77], v66, off
	s_waitcnt vmcnt(22)
	v_lshlrev_b32_e32 v66, 16, v101
	v_and_b32_e32 v67, 0xffff0000, v101
	s_waitcnt vmcnt(21)
	v_pk_fma_f32 v[4:5], v[4:5], v[78:79], v[66:67]
	s_nop 0
	v_cvt_pk_bf16_f32 v66, v4, v5
	global_store_dword v[80:81], v66, off
	s_waitcnt vmcnt(21)
	v_lshlrev_b32_e32 v66, 16, v102
	v_and_b32_e32 v67, 0xffff0000, v102
	s_waitcnt vmcnt(20)
	v_pk_fma_f32 v[4:5], v[4:5], v[82:83], v[66:67]
	s_nop 0
	v_cvt_pk_bf16_f32 v66, v4, v5
	global_store_dword v[84:85], v66, off
	s_waitcnt vmcnt(20)
	v_lshlrev_b32_e32 v66, 16, v103
	v_and_b32_e32 v67, 0xffff0000, v103
	s_waitcnt vmcnt(19)
	v_pk_fma_f32 v[4:5], v[4:5], v[86:87], v[66:67]
	s_nop 0
	v_cvt_pk_bf16_f32 v66, v4, v5
	global_store_dword v[88:89], v66, off
	s_waitcnt vmcnt(19)
	v_lshlrev_b32_e32 v66, 16, v104
	v_and_b32_e32 v67, 0xffff0000, v104
	s_waitcnt vmcnt(18)
	v_pk_fma_f32 v[4:5], v[4:5], v[90:91], v[66:67]
	s_nop 0
	v_cvt_pk_bf16_f32 v66, v4, v5
	global_store_dword v[92:93], v66, off
	s_waitcnt vmcnt(18)
	v_lshlrev_b32_e32 v66, 16, v105
	v_and_b32_e32 v67, 0xffff0000, v105
	s_waitcnt vmcnt(17)
	v_pk_fma_f32 v[4:5], v[4:5], v[94:95], v[66:67]
	s_waitcnt vmcnt(16)
	v_and_b32_e32 v67, 0xffff0000, v106
	v_cvt_pk_bf16_f32 v66, v4, v5
	global_store_dword v[96:97], v66, off
	v_lshlrev_b32_e32 v66, 16, v106
	s_waitcnt vmcnt(16)
	v_pk_fma_f32 v[4:5], v[4:5], v[98:99], v[66:67]
	s_branch .Lmy_scan_item_done
.Lmy_scan_tail_a:
	v_cvt_pk_bf16_f32 v47, v4, v5
	global_store_dword v[6:7], v47, off
	s_waitcnt vmcnt(24)
	v_lshlrev_b32_e32 v6, 16, v9
	v_and_b32_e32 v7, 0xffff0000, v9
	s_waitcnt vmcnt(23)
	v_pk_fma_f32 v[4:5], v[4:5], v[10:11], v[6:7]
	s_nop 0
	v_cvt_pk_bf16_f32 v6, v4, v5
	global_store_dword v[12:13], v6, off
	s_waitcnt vmcnt(23)
	v_lshlrev_b32_e32 v6, 16, v40
	v_and_b32_e32 v7, 0xffff0000, v40
	s_waitcnt vmcnt(22)
	v_pk_fma_f32 v[4:5], v[4:5], v[14:15], v[6:7]
	s_nop 0
	v_cvt_pk_bf16_f32 v6, v4, v5
	global_store_dword v[16:17], v6, off
	s_waitcnt vmcnt(22)
	v_lshlrev_b32_e32 v6, 16, v41
	v_and_b32_e32 v7, 0xffff0000, v41
	s_waitcnt vmcnt(21)
	v_pk_fma_f32 v[4:5], v[4:5], v[18:19], v[6:7]
	s_nop 0
	v_cvt_pk_bf16_f32 v6, v4, v5
	global_store_dword v[20:21], v6, off
	s_waitcnt vmcnt(21)
	v_lshlrev_b32_e32 v6, 16, v42
	v_and_b32_e32 v7, 0xffff0000, v42
	s_waitcnt vmcnt(20)
	v_pk_fma_f32 v[4:5], v[4:5], v[22:23], v[6:7]
	s_nop 0
	v_cvt_pk_bf16_f32 v6, v4, v5
	global_store_dword v[24:25], v6, off
	s_waitcnt vmcnt(20)
	v_lshlrev_b32_e32 v6, 16, v43
	v_and_b32_e32 v7, 0xffff0000, v43
	s_waitcnt vmcnt(19)
	v_pk_fma_f32 v[4:5], v[4:5], v[26:27], v[6:7]
	s_nop 0
	v_cvt_pk_bf16_f32 v6, v4, v5
	global_store_dword v[28:29], v6, off
	s_waitcnt vmcnt(19)
	v_lshlrev_b32_e32 v6, 16, v44
	v_and_b32_e32 v7, 0xffff0000, v44
	s_waitcnt vmcnt(18)
	v_pk_fma_f32 v[4:5], v[4:5], v[30:31], v[6:7]
	s_nop 0
	v_cvt_pk_bf16_f32 v6, v4, v5
	global_store_dword v[32:33], v6, off
	s_waitcnt vmcnt(18)
	v_lshlrev_b32_e32 v6, 16, v45
	v_and_b32_e32 v7, 0xffff0000, v45
	s_waitcnt vmcnt(17)
	v_pk_fma_f32 v[4:5], v[4:5], v[34:35], v[6:7]
	s_waitcnt vmcnt(16)
	v_and_b32_e32 v7, 0xffff0000, v46
	v_cvt_pk_bf16_f32 v6, v4, v5
	global_store_dword v[36:37], v6, off
	v_lshlrev_b32_e32 v6, 16, v46
	s_waitcnt vmcnt(16)
	v_pk_fma_f32 v[4:5], v[4:5], v[38:39], v[6:7]
.Lmy_scan_item_done:
	s_add_i32 s3, s3, s70
	s_cmpk_gt_i32 s3, 0x2ff
	s_cbranch_scc0 .LBB0_323
